# Attention work queue order: neighbourhood-attention items dispatched before the light differential heads (longest-processing-time order)
# baseline (speedup 1.0000x reference)
; __global__ void __launch_bounds__(NWAVES * 64, 2) fwd_megakernel(Args args) {
;     ...
;                         if (tid == 0) qw[0] = __hip_atomic_fetch_add(qctr, 1u, __ATOMIC_RELAXED, __HIP_MEMORY_SCOPE_AGENT);
;                         __syncthreads();
;                         const int item = __builtin_amdgcn_readfirstlane((int)qw[0]);
;                         if (item >= 768) {
;     ...
;                         if (item < 512) {
;                             const int hh = 7 - (item >> 6), c = (item >> 5) & 1, q0 = (item & 31) * 256, d0 = q0 >> 6, pos = q0 + qi;
.LBB0_426:
	s_or_b64 exec, exec, s[2:3]
	v_readlane_b32 s2, v254, 31
	s_waitcnt lgkmcnt(0)
	s_barrier
	v_mov_b32_e32 v0, s2
	ds_read_b32 v0, v0
	s_waitcnt lgkmcnt(0)
	v_readfirstlane_b32 s36, v0
	s_sub_u32 s98, s36, 0x100
	s_cmp_lt_u32 s98, 0x200
	s_cselect_b32 s98, 0x300, 0
	s_xor_b32 s36, s36, s98
	s_cmpk_gt_i32 s36, 0x2ff
	s_cselect_b64 s[2:3], -1, 0
	v_writelane_b32 v254, s2, 58
	s_cmpk_lt_i32 s36, 0x300
	s_nop 0
	v_writelane_b32 v254, s3, 59
	v_writelane_b32 v254, s36, 60
	s_mov_b64 s[2:3], -1
	s_cbranch_scc0 .LBB0_430
	s_and_b64 vcc, exec, s[2:3]
	s_cbranch_vccz .LBB0_421
	s_branch .LBB0_454
